# P5->P6 split seam: dropped the acquire, the wait behind the release atomics and the ignored generation reads on the arrival path (the acquire happens before K-tile 24)
# speedup vs baseline: 1.0090x; 1.0025x over previous
; __device__ __forceinline__ unsigned xb_ld(unsigned* p)              { return __hip_atomic_load(p, __ATOMIC_RELAXED, __HIP_MEMORY_SCOPE_AGENT); }
; __device__ __forceinline__ unsigned xb_add(unsigned* p, unsigned v) { return __hip_atomic_fetch_add(p, v, __ATOMIC_RELAXED, __HIP_MEMORY_SCOPE_AGENT); }
; #define XB_SPIN(cond, bar) do { unsigned _sp = 0; while (cond) { __builtin_amdgcn_s_sleep(1); \
;     if ((++_sp & 255u) == 0u) { if (xb_ld(&(bar)[XB_TMO])) break; if (_sp > XB_SPIN_CAP) { atomicAdd(&(bar)[XB_TMO], 1u); break; } } } } while (0)
; __device__ __forceinline__ void xcd_barrier(const XcdBarrier& b) {
;     ...
;         const unsigned old = xb_add(&bar[XB_XSUB(b.x)], 1u);
;         const unsigned gen = old / nloc;
;         if (old + 1u == (gen + 1u) * nloc) {
;             __builtin_amdgcn_fence(__ATOMIC_RELEASE, "agent");
;             asm volatile("s_waitcnt vmcnt(0)" ::: "memory");
;             const unsigned og = xb_add(&bar[XB_TOP], 1u);
;             const unsigned tg = og / nx;
;             if (og + 1u == (tg + 1u) * nx) xb_add(&bar[XB_TOPGEN], 1u);
;             else XB_SPIN(xb_ld(&bar[XB_TOPGEN]) == tg, bar);
;             __builtin_amdgcn_fence(__ATOMIC_ACQUIRE, "agent");
;             xb_add(&bar[XB_XGEN(b.x)], 1u);
;             asm volatile("s_waitcnt vmcnt(0)" ::: "memory");
;         } else {
;             XB_SPIN(xb_ld(&bar[XB_XGEN(b.x)]) == gen, bar);
.LBB0_703:
	s_or_b64 exec, exec, s[38:39]
	v_cvt_f32_u32_e32 v5, v3
	s_waitcnt vmcnt(0)
	v_readfirstlane_b32 s6, v4
	v_sub_u32_e32 v4, 0, v3
	v_rcp_iflag_f32_e32 v5, v5
	v_add_u32_e32 v6, s6, v0
	v_mul_f32_e32 v5, 0x4f7ffffe, v5
	v_cvt_u32_f32_e32 v5, v5
	v_mul_lo_u32 v0, v4, v5
	v_mul_hi_u32 v0, v5, v0
	v_add_u32_e32 v0, v5, v0
	v_mul_hi_u32 v0, v6, v0
	v_mul_lo_u32 v4, v0, v3
	v_sub_u32_e32 v4, v6, v4
	v_add_u32_e32 v5, 1, v0
	v_cmp_ge_u32_e32 vcc, v4, v3
	s_nop 1
	v_cndmask_b32_e32 v0, v0, v5, vcc
	v_sub_u32_e32 v5, v4, v3
	v_cndmask_b32_e32 v4, v4, v5, vcc
	v_add_u32_e32 v5, 1, v0
	v_cmp_ge_u32_e32 vcc, v4, v3
	v_add_u32_e32 v4, 1, v6
	s_nop 0
	v_cndmask_b32_e32 v0, v0, v5, vcc
	v_mul_lo_u32 v5, v3, v0
	v_add_u32_e32 v3, v5, v3
	v_cmp_ne_u32_e32 vcc, v4, v3
	s_mov_b32 s13, -1
	s_nop 0
	v_writelane_b32 v255, s13, 47
	s_and_saveexec_b64 s[12:13], vcc
	s_xor_b64 s[38:39], exec, s[12:13]
	s_cbranch_execz .LBB0_717
	s_nop 0
	v_readlane_b32 s12, v255, 10
	v_readlane_b32 s13, v255, 11
	s_waitcnt lgkmcnt(0)
	s_nop 3
	s_nop 0
	s_nop 0
	v_cmp_eq_u32_e32 vcc, v2, v0
	v_readfirstlane_b32 s27, v0
	s_nop 1
	v_writelane_b32 v255, s27, 47
	s_mov_b64 vcc, 0
	s_and_saveexec_b64 s[40:41], vcc
	s_cbranch_execz .LBB0_716
	s_mov_b32 s9, 1
	s_mov_b64 s[42:43], 0
	s_branch .LBB0_707

; __device__ __forceinline__ unsigned xb_ld(unsigned* p)              { return __hip_atomic_load(p, __ATOMIC_RELAXED, __HIP_MEMORY_SCOPE_AGENT); }
; __device__ __forceinline__ unsigned xb_add(unsigned* p, unsigned v) { return __hip_atomic_fetch_add(p, v, __ATOMIC_RELAXED, __HIP_MEMORY_SCOPE_AGENT); }
; #define XB_SPIN(cond, bar) do { unsigned _sp = 0; while (cond) { __builtin_amdgcn_s_sleep(1); \
;     if ((++_sp & 255u) == 0u) { if (xb_ld(&(bar)[XB_TMO])) break; if (_sp > XB_SPIN_CAP) { atomicAdd(&(bar)[XB_TMO], 1u); break; } } } } while (0)
; __device__ __forceinline__ void xcd_barrier(const XcdBarrier& b) {
;     ...
;             const unsigned og = xb_add(&bar[XB_TOP], 1u);
;             const unsigned tg = og / nx;
;             if (og + 1u == (tg + 1u) * nx) xb_add(&bar[XB_TOPGEN], 1u);
;             else XB_SPIN(xb_ld(&bar[XB_TOPGEN]) == tg, bar);
.LBB0_720:
	s_or_b64 exec, exec, s[40:41]
	s_waitcnt vmcnt(0)
	v_readfirstlane_b32 s6, v3
	v_sub_u32_e32 v4, 0, v2
	v_readlane_b32 s12, v255, 14
	v_add_u32_e32 v3, s6, v0
	v_cvt_f32_u32_e32 v0, v2
	v_readlane_b32 s13, v255, 15
	s_mov_b64 s[40:41], -1
	v_rcp_iflag_f32_e32 v0, v0
	s_nop 0
	v_mul_f32_e32 v0, 0x4f7ffffe, v0
	v_cvt_u32_f32_e32 v0, v0
	v_mul_lo_u32 v4, v4, v0
	v_mul_hi_u32 v4, v0, v4
	v_add_u32_e32 v0, v0, v4
	v_mul_hi_u32 v0, v3, v0
	v_mul_lo_u32 v4, v0, v2
	v_sub_u32_e32 v4, v3, v4
	v_cmp_ge_u32_e32 vcc, v4, v2
	v_add_u32_e32 v5, 1, v0
	v_add_u32_e32 v3, 1, v3
	v_cndmask_b32_e32 v0, v0, v5, vcc
	v_sub_u32_e32 v5, v4, v2
	v_cndmask_b32_e32 v4, v4, v5, vcc
	v_cmp_ge_u32_e32 vcc, v4, v2
	v_add_u32_e32 v4, 1, v0
	s_nop 0
	v_cndmask_b32_e32 v0, v0, v4, vcc
	v_mul_lo_u32 v4, v2, v0
	v_add_u32_e32 v2, v4, v2
	v_cmp_ne_u32_e32 vcc, v3, v2
	v_mov_b64_e32 v[2:3], s[12:13]
	s_and_saveexec_b64 s[38:39], vcc
	s_cbranch_execz .LBB0_732
	v_readlane_b32 s12, v255, 14
	v_readlane_b32 s13, v255, 15
	s_mov_b64 s[42:43], 0
	s_nop 3
	s_nop 0
	s_nop 0
	v_cmp_eq_u32_e32 vcc, v2, v0
	v_readfirstlane_b32 s27, v0
	s_nop 1
	v_writelane_b32 v255, s27, 47
	s_mov_b64 vcc, 0
	s_and_saveexec_b64 s[40:41], vcc
	s_cbranch_execz .LBB0_731
	s_mov_b32 s9, 1
	s_branch .LBB0_724

; __device__ __forceinline__ unsigned xb_add(unsigned* p, unsigned v) { return __hip_atomic_fetch_add(p, v, __ATOMIC_RELAXED, __HIP_MEMORY_SCOPE_AGENT); }
; __device__ __forceinline__ void xcd_barrier(const XcdBarrier& b) {
;     ...
;             __builtin_amdgcn_fence(__ATOMIC_ACQUIRE, "agent");
;             xb_add(&bar[XB_XGEN(b.x)], 1u);
;             asm volatile("s_waitcnt vmcnt(0)" ::: "memory");
.LBB0_734:
	s_or_b64 exec, exec, s[38:39]
	s_mov_b64 s[38:39], exec
	v_mbcnt_lo_u32_b32 v0, s38, 0
	v_mbcnt_hi_u32_b32 v0, s39, v0
	v_cmp_eq_u32_e32 vcc, 0, v0
	s_nop 0
	s_and_saveexec_b64 s[40:41], vcc
	s_cbranch_execz .LBB0_736
	s_bcnt1_i32_b64 s6, s[38:39]
	v_readlane_b32 s12, v255, 10
	v_mov_b32_e32 v0, s6
	v_readlane_b32 s13, v255, 11
	s_nop 4
	global_atomic_add v1, v0, s[12:13]
.LBB0_736:
	s_or_b64 exec, exec, s[40:41]
	s_nop 0
	s_nop 0
